# post_z head-norm slab: 32 row loads up front + DPP wave reductions; rope-q slab: loads batched 16 rows at a time
# speedup vs baseline: 1.0168x; 1.0168x over previous
; DI bf16_t f2bf(float a) { return (bf16_t)(pack2(a, 0.f) & 0xffffu); }
; DI float bf2f(bf16_t h) { return __uint_as_float(((unsigned)h) << 16); }
; DI void post_z(const Params& p, int layer) {
;     ...
;     } else if (slab < 20) {
;       const int h = slab - 16;
;       const int colbase = C_RQ + h * 128;
;       float x1[32], x2[32];
; #pragma unroll
;       for (int i = 0; i < 32; ++i) {
;         const bf16_t* p1 = zr + (size_t)i * ZS + colbase + lane;
;         x1[i] = bf2f(p1[0]);
;         x2[i] = bf2f(p1[64]);
;       }
; #pragma unroll
;       for (int i = 0; i < 32; ++i) {
;         bf16_t* p1 = zr + (size_t)i * ZS + colbase + lane;
;         float2 cs = rope[(spos + i) * 64 + lane];
;         p1[0] = f2bf(x1[i] * cs.x - x2[i] * cs.y);
;         p1[64] = f2bf(x1[i] * cs.y + x2[i] * cs.x);
;       }
.LBB0_193:
	s_andn2_saveexec_b64 s[0:1], s[0:1]
	s_cbranch_execz .LBB0_195
	s_movk_i32 s5, 0xee00
	v_mul_lo_u32 v0, v43, s5
	s_movk_i32 s5, 0xa00
	v_add3_u32 v0, v38, v0, s5
	v_lshl_add_u64 v[2:3], v[0:1], 1, v[6:7]
	v_lshlrev_b32_e32 v0, 1, v32
	v_lshl_add_u64 v[2:3], v[2:3], 0, v[0:1]
	v_readlane_b32 s12, v252, 10
	v_readlane_b32 s13, v252, 11
	s_mov_b32 s98, 0x2a30
	s_mov_b32 s99, 0
	v_mov_b64_e32 v[20:21], v[2:3]
	v_mov_b64_e32 v[22:23], v[2:3]
	v_mov_b32_e32 v24, v4
	global_load_ushort v68, v[20:21], off offset:-1488
	global_load_ushort v84, v[20:21], off offset:-1360
	v_lshl_add_u64 v[20:21], v[20:21], 0, s[98:99]
	global_load_dwordx2 v[216:217], v24, s[12:13]
	global_load_ushort v69, v[20:21], off offset:-1488
	global_load_ushort v85, v[20:21], off offset:-1360
	v_lshl_add_u64 v[20:21], v[20:21], 0, s[98:99]
	global_load_dwordx2 v[218:219], v24, s[12:13] offset:512
	global_load_ushort v70, v[20:21], off offset:-1488
	global_load_ushort v86, v[20:21], off offset:-1360
	v_lshl_add_u64 v[20:21], v[20:21], 0, s[98:99]
	global_load_dwordx2 v[220:221], v24, s[12:13] offset:1024
	global_load_ushort v71, v[20:21], off offset:-1488
	global_load_ushort v87, v[20:21], off offset:-1360
	v_lshl_add_u64 v[20:21], v[20:21], 0, s[98:99]
	global_load_dwordx2 v[222:223], v24, s[12:13] offset:1536
	global_load_ushort v72, v[20:21], off offset:-1488
	global_load_ushort v88, v[20:21], off offset:-1360
	v_lshl_add_u64 v[20:21], v[20:21], 0, s[98:99]
	global_load_dwordx2 v[224:225], v24, s[12:13] offset:2048
	global_load_ushort v73, v[20:21], off offset:-1488
	global_load_ushort v89, v[20:21], off offset:-1360
	v_lshl_add_u64 v[20:21], v[20:21], 0, s[98:99]
	global_load_dwordx2 v[226:227], v24, s[12:13] offset:2560
	global_load_ushort v74, v[20:21], off offset:-1488
	global_load_ushort v90, v[20:21], off offset:-1360
	v_lshl_add_u64 v[20:21], v[20:21], 0, s[98:99]
	global_load_dwordx2 v[228:229], v24, s[12:13] offset:3072
	global_load_ushort v75, v[20:21], off offset:-1488
	global_load_ushort v91, v[20:21], off offset:-1360
	v_lshl_add_u64 v[20:21], v[20:21], 0, s[98:99]
	global_load_dwordx2 v[230:231], v24, s[12:13] offset:3584
	v_add_u32_e32 v24, 0x1000, v24
	global_load_ushort v76, v[20:21], off offset:-1488
	global_load_ushort v92, v[20:21], off offset:-1360
	v_lshl_add_u64 v[20:21], v[20:21], 0, s[98:99]
	global_load_dwordx2 v[232:233], v24, s[12:13]
	global_load_ushort v77, v[20:21], off offset:-1488
	global_load_ushort v93, v[20:21], off offset:-1360
	v_lshl_add_u64 v[20:21], v[20:21], 0, s[98:99]
	global_load_dwordx2 v[234:235], v24, s[12:13] offset:512
	global_load_ushort v78, v[20:21], off offset:-1488
	global_load_ushort v94, v[20:21], off offset:-1360
	v_lshl_add_u64 v[20:21], v[20:21], 0, s[98:99]
	global_load_dwordx2 v[236:237], v24, s[12:13] offset:1024
	global_load_ushort v79, v[20:21], off offset:-1488
	global_load_ushort v95, v[20:21], off offset:-1360
	v_lshl_add_u64 v[20:21], v[20:21], 0, s[98:99]
	global_load_dwordx2 v[238:239], v24, s[12:13] offset:1536
	global_load_ushort v80, v[20:21], off offset:-1488
	global_load_ushort v96, v[20:21], off offset:-1360
	v_lshl_add_u64 v[20:21], v[20:21], 0, s[98:99]
	global_load_dwordx2 v[240:241], v24, s[12:13] offset:2048
	global_load_ushort v81, v[20:21], off offset:-1488
	global_load_ushort v97, v[20:21], off offset:-1360
	v_lshl_add_u64 v[20:21], v[20:21], 0, s[98:99]
	global_load_dwordx2 v[242:243], v24, s[12:13] offset:2560
	global_load_ushort v82, v[20:21], off offset:-1488
	global_load_ushort v98, v[20:21], off offset:-1360
	v_lshl_add_u64 v[20:21], v[20:21], 0, s[98:99]
	global_load_dwordx2 v[244:245], v24, s[12:13] offset:3072
	global_load_ushort v83, v[20:21], off offset:-1488
	global_load_ushort v99, v[20:21], off offset:-1360
	v_lshl_add_u64 v[20:21], v[20:21], 0, s[98:99]
	global_load_dwordx2 v[246:247], v24, s[12:13] offset:3584
	v_add_u32_e32 v24, 0x1000, v24
	s_waitcnt vmcnt(0)
	v_lshlrev_b32_e32 v68, 16, v68
	v_lshlrev_b32_e32 v84, 16, v84
	v_lshlrev_b32_e32 v69, 16, v69
	v_lshlrev_b32_e32 v85, 16, v85
	v_lshlrev_b32_e32 v70, 16, v70
	v_lshlrev_b32_e32 v86, 16, v86
	v_lshlrev_b32_e32 v71, 16, v71
	v_lshlrev_b32_e32 v87, 16, v87
	v_lshlrev_b32_e32 v72, 16, v72
	v_lshlrev_b32_e32 v88, 16, v88
	v_lshlrev_b32_e32 v73, 16, v73
	v_lshlrev_b32_e32 v89, 16, v89
	v_lshlrev_b32_e32 v74, 16, v74
	v_lshlrev_b32_e32 v90, 16, v90
	v_lshlrev_b32_e32 v75, 16, v75
	v_lshlrev_b32_e32 v91, 16, v91
	v_lshlrev_b32_e32 v76, 16, v76
	v_lshlrev_b32_e32 v92, 16, v92
	v_lshlrev_b32_e32 v77, 16, v77
	v_lshlrev_b32_e32 v93, 16, v93
	v_lshlrev_b32_e32 v78, 16, v78
	v_lshlrev_b32_e32 v94, 16, v94
	v_lshlrev_b32_e32 v79, 16, v79
	v_lshlrev_b32_e32 v95, 16, v95
	v_lshlrev_b32_e32 v80, 16, v80
	v_lshlrev_b32_e32 v96, 16, v96
	v_lshlrev_b32_e32 v81, 16, v81
	v_lshlrev_b32_e32 v97, 16, v97
	v_lshlrev_b32_e32 v82, 16, v82
	v_lshlrev_b32_e32 v98, 16, v98
	v_lshlrev_b32_e32 v83, 16, v83
	v_lshlrev_b32_e32 v99, 16, v99
	v_mul_f32_e32 v100, v217, v84
	v_mul_f32_e32 v101, v219, v85
	v_mul_f32_e32 v102, v221, v86
	v_mul_f32_e32 v103, v223, v87
	v_mul_f32_e32 v104, v225, v88
	v_mul_f32_e32 v105, v227, v89
	v_mul_f32_e32 v106, v229, v90
	v_mul_f32_e32 v107, v231, v91
	v_mul_f32_e32 v108, v233, v92
	v_mul_f32_e32 v109, v235, v93
	v_mul_f32_e32 v110, v237, v94
	v_mul_f32_e32 v111, v239, v95
	v_mul_f32_e32 v112, v241, v96
	v_mul_f32_e32 v113, v243, v97
	v_mul_f32_e32 v114, v245, v98
	v_mul_f32_e32 v115, v247, v99
	v_mul_f32_e32 v127, v217, v68
	v_mul_f32_e32 v128, v219, v69
	v_mul_f32_e32 v129, v221, v70
	v_mul_f32_e32 v130, v223, v71
	v_mul_f32_e32 v131, v225, v72
	v_mul_f32_e32 v132, v227, v73
	v_mul_f32_e32 v133, v229, v74
; DI bf16_t f2bf(float a) { return (bf16_t)(pack2(a, 0.f) & 0xffffu); }
; DI float bf2f(bf16_t h) { return __uint_as_float(((unsigned)h) << 16); }
; DI void post_z(const Params& p, int layer) {
;     ...
;       for (int i = 0; i < 32; ++i) {
;         const bf16_t* p1 = zr + (size_t)i * ZS + colbase + lane;
;         x1[i] = bf2f(p1[0]);
;         x2[i] = bf2f(p1[64]);
;       }
; #pragma unroll
;       for (int i = 0; i < 32; ++i) {
;         bf16_t* p1 = zr + (size_t)i * ZS + colbase + lane;
;         float2 cs = rope[(spos + i) * 64 + lane];
;         p1[0] = f2bf(x1[i] * cs.x - x2[i] * cs.y);
;         p1[64] = f2bf(x1[i] * cs.y + x2[i] * cs.x);
;       }
	v_mul_f32_e32 v134, v231, v75
	v_mul_f32_e32 v135, v233, v76
	v_mul_f32_e32 v136, v235, v77
	v_mul_f32_e32 v137, v237, v78
	v_mul_f32_e32 v138, v239, v79
	v_mul_f32_e32 v139, v241, v80
	v_mul_f32_e32 v140, v243, v81
	v_mul_f32_e32 v141, v245, v82
	v_mul_f32_e32 v142, v247, v83
	v_fma_f32 v68, v216, v68, -v100
	v_fma_f32 v69, v218, v69, -v101
	v_fma_f32 v70, v220, v70, -v102
	v_fma_f32 v71, v222, v71, -v103
	v_fma_f32 v72, v224, v72, -v104
	v_fma_f32 v73, v226, v73, -v105
	v_fma_f32 v74, v228, v74, -v106
	v_fma_f32 v75, v230, v75, -v107
	v_fma_f32 v76, v232, v76, -v108
	v_fma_f32 v77, v234, v77, -v109
	v_fma_f32 v78, v236, v78, -v110
	v_fma_f32 v79, v238, v79, -v111
	v_fma_f32 v80, v240, v80, -v112
	v_fma_f32 v81, v242, v81, -v113
	v_fma_f32 v82, v244, v82, -v114
	v_fma_f32 v83, v246, v83, -v115
	v_fmac_f32_e32 v127, v216, v84
	v_fmac_f32_e32 v128, v218, v85
	v_fmac_f32_e32 v129, v220, v86
	v_fmac_f32_e32 v130, v222, v87
	v_fmac_f32_e32 v131, v224, v88
	v_fmac_f32_e32 v132, v226, v89
	v_fmac_f32_e32 v133, v228, v90
	v_fmac_f32_e32 v134, v230, v91
	v_fmac_f32_e32 v135, v232, v92
	v_fmac_f32_e32 v136, v234, v93
	v_fmac_f32_e32 v137, v236, v94
	v_fmac_f32_e32 v138, v238, v95
	v_fmac_f32_e32 v139, v240, v96
	v_fmac_f32_e32 v140, v242, v97
	v_fmac_f32_e32 v141, v244, v98
	v_fmac_f32_e32 v142, v246, v99
	v_cvt_pk_bf16_f32 v68, v68, s0
	v_cvt_pk_bf16_f32 v127, v127, s0
	v_cvt_pk_bf16_f32 v69, v69, s0
	v_cvt_pk_bf16_f32 v128, v128, s0
	v_cvt_pk_bf16_f32 v70, v70, s0
	v_cvt_pk_bf16_f32 v129, v129, s0
	v_cvt_pk_bf16_f32 v71, v71, s0
	v_cvt_pk_bf16_f32 v130, v130, s0
	v_cvt_pk_bf16_f32 v72, v72, s0
	v_cvt_pk_bf16_f32 v131, v131, s0
	v_cvt_pk_bf16_f32 v73, v73, s0
	v_cvt_pk_bf16_f32 v132, v132, s0
	v_cvt_pk_bf16_f32 v74, v74, s0
	v_cvt_pk_bf16_f32 v133, v133, s0
	v_cvt_pk_bf16_f32 v75, v75, s0
	v_cvt_pk_bf16_f32 v134, v134, s0
	v_cvt_pk_bf16_f32 v76, v76, s0
	v_cvt_pk_bf16_f32 v135, v135, s0
	v_cvt_pk_bf16_f32 v77, v77, s0
	v_cvt_pk_bf16_f32 v136, v136, s0
	v_cvt_pk_bf16_f32 v78, v78, s0
	v_cvt_pk_bf16_f32 v137, v137, s0
	v_cvt_pk_bf16_f32 v79, v79, s0
	v_cvt_pk_bf16_f32 v138, v138, s0
	v_cvt_pk_bf16_f32 v80, v80, s0
	v_cvt_pk_bf16_f32 v139, v139, s0
	v_cvt_pk_bf16_f32 v81, v81, s0
	v_cvt_pk_bf16_f32 v140, v140, s0
	v_cvt_pk_bf16_f32 v82, v82, s0
	v_cvt_pk_bf16_f32 v141, v141, s0
	v_cvt_pk_bf16_f32 v83, v83, s0
	v_cvt_pk_bf16_f32 v142, v142, s0
	global_store_short v[22:23], v68, off offset:-1488
	global_store_short v[22:23], v127, off offset:-1360
	v_lshl_add_u64 v[22:23], v[22:23], 0, s[98:99]
	global_store_short v[22:23], v69, off offset:-1488
	global_store_short v[22:23], v128, off offset:-1360
	v_lshl_add_u64 v[22:23], v[22:23], 0, s[98:99]
	global_store_short v[22:23], v70, off offset:-1488
	global_store_short v[22:23], v129, off offset:-1360
	v_lshl_add_u64 v[22:23], v[22:23], 0, s[98:99]
	global_store_short v[22:23], v71, off offset:-1488
	global_store_short v[22:23], v130, off offset:-1360
	v_lshl_add_u64 v[22:23], v[22:23], 0, s[98:99]
	global_store_short v[22:23], v72, off offset:-1488
	global_store_short v[22:23], v131, off offset:-1360
	v_lshl_add_u64 v[22:23], v[22:23], 0, s[98:99]
	global_store_short v[22:23], v73, off offset:-1488
	global_store_short v[22:23], v132, off offset:-1360
	v_lshl_add_u64 v[22:23], v[22:23], 0, s[98:99]
	global_store_short v[22:23], v74, off offset:-1488
	global_store_short v[22:23], v133, off offset:-1360
	v_lshl_add_u64 v[22:23], v[22:23], 0, s[98:99]
	global_store_short v[22:23], v75, off offset:-1488
	global_store_short v[22:23], v134, off offset:-1360
	v_lshl_add_u64 v[22:23], v[22:23], 0, s[98:99]
	global_store_short v[22:23], v76, off offset:-1488
	global_store_short v[22:23], v135, off offset:-1360
	v_lshl_add_u64 v[22:23], v[22:23], 0, s[98:99]
	global_store_short v[22:23], v77, off offset:-1488
	global_store_short v[22:23], v136, off offset:-1360
	v_lshl_add_u64 v[22:23], v[22:23], 0, s[98:99]
	global_store_short v[22:23], v78, off offset:-1488
	global_store_short v[22:23], v137, off offset:-1360
	v_lshl_add_u64 v[22:23], v[22:23], 0, s[98:99]
	global_store_short v[22:23], v79, off offset:-1488
	global_store_short v[22:23], v138, off offset:-1360
	v_lshl_add_u64 v[22:23], v[22:23], 0, s[98:99]
	global_store_short v[22:23], v80, off offset:-1488
	global_store_short v[22:23], v139, off offset:-1360
	v_lshl_add_u64 v[22:23], v[22:23], 0, s[98:99]
	global_store_short v[22:23], v81, off offset:-1488
	global_store_short v[22:23], v140, off offset:-1360
	v_lshl_add_u64 v[22:23], v[22:23], 0, s[98:99]
	global_store_short v[22:23], v82, off offset:-1488
	global_store_short v[22:23], v141, off offset:-1360
	v_lshl_add_u64 v[22:23], v[22:23], 0, s[98:99]
	global_store_short v[22:23], v83, off offset:-1488
	global_store_short v[22:23], v142, off offset:-1360
	v_lshl_add_u64 v[22:23], v[22:23], 0, s[98:99]
	global_load_ushort v68, v[20:21], off offset:-1488
	global_load_ushort v84, v[20:21], off offset:-1360
	v_lshl_add_u64 v[20:21], v[20:21], 0, s[98:99]
	global_load_dwordx2 v[216:217], v24, s[12:13]
	global_load_ushort v69, v[20:21], off offset:-1488
	global_load_ushort v85, v[20:21], off offset:-1360
	v_lshl_add_u64 v[20:21], v[20:21], 0, s[98:99]
	global_load_dwordx2 v[218:219], v24, s[12:13] offset:512
	global_load_ushort v70, v[20:21], off offset:-1488
	global_load_ushort v86, v[20:21], off offset:-1360
	v_lshl_add_u64 v[20:21], v[20:21], 0, s[98:99]
	global_load_dwordx2 v[220:221], v24, s[12:13] offset:1024
	global_load_ushort v71, v[20:21], off offset:-1488
	global_load_ushort v87, v[20:21], off offset:-1360
	v_lshl_add_u64 v[20:21], v[20:21], 0, s[98:99]
	global_load_dwordx2 v[222:223], v24, s[12:13] offset:1536
; DI float bf2f(bf16_t h) { return __uint_as_float(((unsigned)h) << 16); }
; DI void post_z(const Params& p, int layer) {
;     ...
;       for (int i = 0; i < 32; ++i) {
;         const bf16_t* p1 = zr + (size_t)i * ZS + colbase + lane;
;         x1[i] = bf2f(p1[0]);
;         x2[i] = bf2f(p1[64]);
;       }
	global_load_ushort v72, v[20:21], off offset:-1488
	global_load_ushort v88, v[20:21], off offset:-1360
	v_lshl_add_u64 v[20:21], v[20:21], 0, s[98:99]
	global_load_dwordx2 v[224:225], v24, s[12:13] offset:2048
	global_load_ushort v73, v[20:21], off offset:-1488
	global_load_ushort v89, v[20:21], off offset:-1360
	v_lshl_add_u64 v[20:21], v[20:21], 0, s[98:99]
	global_load_dwordx2 v[226:227], v24, s[12:13] offset:2560
	global_load_ushort v74, v[20:21], off offset:-1488
	global_load_ushort v90, v[20:21], off offset:-1360
	v_lshl_add_u64 v[20:21], v[20:21], 0, s[98:99]
	global_load_dwordx2 v[228:229], v24, s[12:13] offset:3072
	global_load_ushort v75, v[20:21], off offset:-1488
	global_load_ushort v91, v[20:21], off offset:-1360
	v_lshl_add_u64 v[20:21], v[20:21], 0, s[98:99]
	global_load_dwordx2 v[230:231], v24, s[12:13] offset:3584
	v_add_u32_e32 v24, 0x1000, v24
	global_load_ushort v76, v[20:21], off offset:-1488
	global_load_ushort v92, v[20:21], off offset:-1360
	v_lshl_add_u64 v[20:21], v[20:21], 0, s[98:99]
	global_load_dwordx2 v[232:233], v24, s[12:13]
	global_load_ushort v77, v[20:21], off offset:-1488
	global_load_ushort v93, v[20:21], off offset:-1360
	v_lshl_add_u64 v[20:21], v[20:21], 0, s[98:99]
	global_load_dwordx2 v[234:235], v24, s[12:13] offset:512
	global_load_ushort v78, v[20:21], off offset:-1488
	global_load_ushort v94, v[20:21], off offset:-1360
	v_lshl_add_u64 v[20:21], v[20:21], 0, s[98:99]
	global_load_dwordx2 v[236:237], v24, s[12:13] offset:1024
	global_load_ushort v79, v[20:21], off offset:-1488
	global_load_ushort v95, v[20:21], off offset:-1360
	v_lshl_add_u64 v[20:21], v[20:21], 0, s[98:99]
	global_load_dwordx2 v[238:239], v24, s[12:13] offset:1536
	global_load_ushort v80, v[20:21], off offset:-1488
	global_load_ushort v96, v[20:21], off offset:-1360
	v_lshl_add_u64 v[20:21], v[20:21], 0, s[98:99]
	global_load_dwordx2 v[240:241], v24, s[12:13] offset:2048
	global_load_ushort v81, v[20:21], off offset:-1488
	global_load_ushort v97, v[20:21], off offset:-1360
	v_lshl_add_u64 v[20:21], v[20:21], 0, s[98:99]
	global_load_dwordx2 v[242:243], v24, s[12:13] offset:2560
	global_load_ushort v82, v[20:21], off offset:-1488
	global_load_ushort v98, v[20:21], off offset:-1360
	v_lshl_add_u64 v[20:21], v[20:21], 0, s[98:99]
	global_load_dwordx2 v[244:245], v24, s[12:13] offset:3072
	global_load_ushort v83, v[20:21], off offset:-1488
	global_load_ushort v99, v[20:21], off offset:-1360
	v_lshl_add_u64 v[20:21], v[20:21], 0, s[98:99]
	global_load_dwordx2 v[246:247], v24, s[12:13] offset:3584
	v_add_u32_e32 v24, 0x1000, v24
	s_waitcnt vmcnt(0)
; DI bf16_t f2bf(float a) { return (bf16_t)(pack2(a, 0.f) & 0xffffu); }
; DI void post_z(const Params& p, int layer) {
;     ...
; #pragma unroll
;       for (int i = 0; i < 32; ++i) {
;         bf16_t* p1 = zr + (size_t)i * ZS + colbase + lane;
;         float2 cs = rope[(spos + i) * 64 + lane];
;         p1[0] = f2bf(x1[i] * cs.x - x2[i] * cs.y);
;         p1[64] = f2bf(x1[i] * cs.y + x2[i] * cs.x);
;       }
	v_lshlrev_b32_e32 v68, 16, v68
	v_lshlrev_b32_e32 v84, 16, v84
	v_lshlrev_b32_e32 v69, 16, v69
	v_lshlrev_b32_e32 v85, 16, v85
	v_lshlrev_b32_e32 v70, 16, v70
	v_lshlrev_b32_e32 v86, 16, v86
	v_lshlrev_b32_e32 v71, 16, v71
	v_lshlrev_b32_e32 v87, 16, v87
	v_lshlrev_b32_e32 v72, 16, v72
	v_lshlrev_b32_e32 v88, 16, v88
	v_lshlrev_b32_e32 v73, 16, v73
	v_lshlrev_b32_e32 v89, 16, v89
	v_lshlrev_b32_e32 v74, 16, v74
	v_lshlrev_b32_e32 v90, 16, v90
	v_lshlrev_b32_e32 v75, 16, v75
	v_lshlrev_b32_e32 v91, 16, v91
	v_lshlrev_b32_e32 v76, 16, v76
	v_lshlrev_b32_e32 v92, 16, v92
	v_lshlrev_b32_e32 v77, 16, v77
	v_lshlrev_b32_e32 v93, 16, v93
	v_lshlrev_b32_e32 v78, 16, v78
	v_lshlrev_b32_e32 v94, 16, v94
	v_lshlrev_b32_e32 v79, 16, v79
	v_lshlrev_b32_e32 v95, 16, v95
	v_lshlrev_b32_e32 v80, 16, v80
	v_lshlrev_b32_e32 v96, 16, v96
	v_lshlrev_b32_e32 v81, 16, v81
	v_lshlrev_b32_e32 v97, 16, v97
	v_lshlrev_b32_e32 v82, 16, v82
	v_lshlrev_b32_e32 v98, 16, v98
	v_lshlrev_b32_e32 v83, 16, v83
	v_lshlrev_b32_e32 v99, 16, v99
	v_mul_f32_e32 v100, v217, v84
	v_mul_f32_e32 v101, v219, v85
	v_mul_f32_e32 v102, v221, v86
	v_mul_f32_e32 v103, v223, v87
	v_mul_f32_e32 v104, v225, v88
	v_mul_f32_e32 v105, v227, v89
	v_mul_f32_e32 v106, v229, v90
	v_mul_f32_e32 v107, v231, v91
	v_mul_f32_e32 v108, v233, v92
	v_mul_f32_e32 v109, v235, v93
	v_mul_f32_e32 v110, v237, v94
	v_mul_f32_e32 v111, v239, v95
	v_mul_f32_e32 v112, v241, v96
	v_mul_f32_e32 v113, v243, v97
	v_mul_f32_e32 v114, v245, v98
	v_mul_f32_e32 v115, v247, v99
	v_mul_f32_e32 v127, v217, v68
	v_mul_f32_e32 v128, v219, v69
	v_mul_f32_e32 v129, v221, v70
	v_mul_f32_e32 v130, v223, v71
	v_mul_f32_e32 v131, v225, v72
	v_mul_f32_e32 v132, v227, v73
	v_mul_f32_e32 v133, v229, v74
	v_mul_f32_e32 v134, v231, v75
	v_mul_f32_e32 v135, v233, v76
	v_mul_f32_e32 v136, v235, v77
	v_mul_f32_e32 v137, v237, v78
	v_mul_f32_e32 v138, v239, v79
	v_mul_f32_e32 v139, v241, v80
	v_mul_f32_e32 v140, v243, v81
	v_mul_f32_e32 v141, v245, v82
	v_mul_f32_e32 v142, v247, v83
	v_fma_f32 v68, v216, v68, -v100
	v_fma_f32 v69, v218, v69, -v101
	v_fma_f32 v70, v220, v70, -v102
	v_fma_f32 v71, v222, v71, -v103
	v_fma_f32 v72, v224, v72, -v104
	v_fma_f32 v73, v226, v73, -v105
	v_fma_f32 v74, v228, v74, -v106
	v_fma_f32 v75, v230, v75, -v107
	v_fma_f32 v76, v232, v76, -v108
	v_fma_f32 v77, v234, v77, -v109
	v_fma_f32 v78, v236, v78, -v110
	v_fma_f32 v79, v238, v79, -v111
	v_fma_f32 v80, v240, v80, -v112
	v_fma_f32 v81, v242, v81, -v113
	v_fma_f32 v82, v244, v82, -v114
	v_fma_f32 v83, v246, v83, -v115
	v_fmac_f32_e32 v127, v216, v84
	v_fmac_f32_e32 v128, v218, v85
	v_fmac_f32_e32 v129, v220, v86
	v_fmac_f32_e32 v130, v222, v87
	v_fmac_f32_e32 v131, v224, v88
	v_fmac_f32_e32 v132, v226, v89
	v_fmac_f32_e32 v133, v228, v90
	v_fmac_f32_e32 v134, v230, v91
	v_fmac_f32_e32 v135, v232, v92
	v_fmac_f32_e32 v136, v234, v93
	v_fmac_f32_e32 v137, v236, v94
	v_fmac_f32_e32 v138, v238, v95
	v_fmac_f32_e32 v139, v240, v96
	v_fmac_f32_e32 v140, v242, v97
	v_fmac_f32_e32 v141, v244, v98
	v_fmac_f32_e32 v142, v246, v99
	v_cvt_pk_bf16_f32 v68, v68, s0
	v_cvt_pk_bf16_f32 v127, v127, s0
	v_cvt_pk_bf16_f32 v69, v69, s0
	v_cvt_pk_bf16_f32 v128, v128, s0
	v_cvt_pk_bf16_f32 v70, v70, s0
	v_cvt_pk_bf16_f32 v129, v129, s0
	v_cvt_pk_bf16_f32 v71, v71, s0
	v_cvt_pk_bf16_f32 v130, v130, s0
	v_cvt_pk_bf16_f32 v72, v72, s0
	v_cvt_pk_bf16_f32 v131, v131, s0
	v_cvt_pk_bf16_f32 v73, v73, s0
	v_cvt_pk_bf16_f32 v132, v132, s0
	v_cvt_pk_bf16_f32 v74, v74, s0
	v_cvt_pk_bf16_f32 v133, v133, s0
	v_cvt_pk_bf16_f32 v75, v75, s0
	v_cvt_pk_bf16_f32 v134, v134, s0
	v_cvt_pk_bf16_f32 v76, v76, s0
	v_cvt_pk_bf16_f32 v135, v135, s0
	v_cvt_pk_bf16_f32 v77, v77, s0
	v_cvt_pk_bf16_f32 v136, v136, s0
	v_cvt_pk_bf16_f32 v78, v78, s0
	v_cvt_pk_bf16_f32 v137, v137, s0
	v_cvt_pk_bf16_f32 v79, v79, s0
	v_cvt_pk_bf16_f32 v138, v138, s0
	v_cvt_pk_bf16_f32 v80, v80, s0
	v_cvt_pk_bf16_f32 v139, v139, s0
	v_cvt_pk_bf16_f32 v81, v81, s0
	v_cvt_pk_bf16_f32 v140, v140, s0
	v_cvt_pk_bf16_f32 v82, v82, s0
	v_cvt_pk_bf16_f32 v141, v141, s0
	v_cvt_pk_bf16_f32 v83, v83, s0
	v_cvt_pk_bf16_f32 v142, v142, s0
	global_store_short v[22:23], v68, off offset:-1488
	global_store_short v[22:23], v127, off offset:-1360
	v_lshl_add_u64 v[22:23], v[22:23], 0, s[98:99]
	global_store_short v[22:23], v69, off offset:-1488
	global_store_short v[22:23], v128, off offset:-1360
	v_lshl_add_u64 v[22:23], v[22:23], 0, s[98:99]
	global_store_short v[22:23], v70, off offset:-1488
	global_store_short v[22:23], v129, off offset:-1360
	v_lshl_add_u64 v[22:23], v[22:23], 0, s[98:99]
	global_store_short v[22:23], v71, off offset:-1488
	global_store_short v[22:23], v130, off offset:-1360
	v_lshl_add_u64 v[22:23], v[22:23], 0, s[98:99]
	global_store_short v[22:23], v72, off offset:-1488
	global_store_short v[22:23], v131, off offset:-1360
	v_lshl_add_u64 v[22:23], v[22:23], 0, s[98:99]
	global_store_short v[22:23], v73, off offset:-1488
	global_store_short v[22:23], v132, off offset:-1360
	v_lshl_add_u64 v[22:23], v[22:23], 0, s[98:99]
	global_store_short v[22:23], v74, off offset:-1488
	global_store_short v[22:23], v133, off offset:-1360
	v_lshl_add_u64 v[22:23], v[22:23], 0, s[98:99]
	global_store_short v[22:23], v75, off offset:-1488
	global_store_short v[22:23], v134, off offset:-1360
	v_lshl_add_u64 v[22:23], v[22:23], 0, s[98:99]
	global_store_short v[22:23], v76, off offset:-1488
	global_store_short v[22:23], v135, off offset:-1360
	v_lshl_add_u64 v[22:23], v[22:23], 0, s[98:99]
	global_store_short v[22:23], v77, off offset:-1488
	global_store_short v[22:23], v136, off offset:-1360
	v_lshl_add_u64 v[22:23], v[22:23], 0, s[98:99]
	global_store_short v[22:23], v78, off offset:-1488
	global_store_short v[22:23], v137, off offset:-1360
	v_lshl_add_u64 v[22:23], v[22:23], 0, s[98:99]
	global_store_short v[22:23], v79, off offset:-1488
	global_store_short v[22:23], v138, off offset:-1360
	v_lshl_add_u64 v[22:23], v[22:23], 0, s[98:99]
	global_store_short v[22:23], v80, off offset:-1488
	global_store_short v[22:23], v139, off offset:-1360
	v_lshl_add_u64 v[22:23], v[22:23], 0, s[98:99]
	global_store_short v[22:23], v81, off offset:-1488
	global_store_short v[22:23], v140, off offset:-1360
	v_lshl_add_u64 v[22:23], v[22:23], 0, s[98:99]
	global_store_short v[22:23], v82, off offset:-1488
	global_store_short v[22:23], v141, off offset:-1360
	v_lshl_add_u64 v[22:23], v[22:23], 0, s[98:99]
	global_store_short v[22:23], v83, off offset:-1488
	global_store_short v[22:23], v142, off offset:-1360
	v_lshl_add_u64 v[22:23], v[22:23], 0, s[98:99]

; DI bf16_t f2bf(float a) { return (bf16_t)(pack2(a, 0.f) & 0xffffu); }
; DI float bf2f(bf16_t h) { return __uint_as_float(((unsigned)h) << 16); }
; DI void post_z(const Params& p, int layer) {
;     ...
;       int colbase; const float* g; float sc;
;       if (slab < 8) { colbase = C_Q + slab * 64; g = qn; sc = 0.125f; }
;       else if (slab < 10) { colbase = C_KS + (slab - 8) * 64; g = kn; sc = 1.f; }
;       else { colbase = C_KW + (slab - 10) * 64; g = kn; sc = 1.f; }
;       const float gv = g[lane] * sc;
;       float v[32];
; #pragma unroll
;       for (int i = 0; i < 32; ++i) v[i] = bf2f(zr[(size_t)i * ZS + colbase + lane]);
; #pragma unroll
;       for (int i = 0; i < 32; ++i) {
;         float ss = wave_sum(v[i] * v[i], lane);
;         float rs = rsqrtf(ss * (1.f / 64.f) + 1e-6f);
;         zr[(size_t)i * ZS + colbase + lane] = f2bf(v[i] * rs * gv);
;       }
.LBB0_210:
	s_or_saveexec_b64 s[2:3], s[2:3]
	v_mov_b32_e32 v10, 1.0
	v_mov_b64_e32 v[8:9], s[10:11]
	s_xor_b64 exec, exec, s[2:3]
	v_lshlrev_b32_e32 v4, 6, v2
	v_mov_b32_e32 v10, 0x3e000000
	v_mov_b64_e32 v[8:9], s[40:41]
	s_or_b64 exec, exec, s[2:3]
	v_lshlrev_b32_e32 v0, 2, v32
	v_lshl_add_u64 v[2:3], v[8:9], 0, v[0:1]
	v_ashrrev_i32_e32 v5, 31, v4
	global_load_dword v11, v[2:3], off
	v_lshl_add_u64 v[2:3], v[4:5], 1, v[6:7]
	v_lshlrev_b32_e32 v0, 1, v32
	v_lshl_add_u64 v[78:79], v[2:3], 0, v[0:1]
	s_mov_b32 s98, 0x2a30
	s_mov_b32 s99, 0
	s_mov_b32 s12, 0x3c800000
	v_mov_b64_e32 v[116:117], v[78:79]
	v_mov_b64_e32 v[118:119], v[78:79]
	global_load_ushort v127, v[116:117], off
	v_lshl_add_u64 v[116:117], v[116:117], 0, s[98:99]
	global_load_ushort v128, v[116:117], off
	v_lshl_add_u64 v[116:117], v[116:117], 0, s[98:99]
	global_load_ushort v129, v[116:117], off
	v_lshl_add_u64 v[116:117], v[116:117], 0, s[98:99]
	global_load_ushort v130, v[116:117], off
	v_lshl_add_u64 v[116:117], v[116:117], 0, s[98:99]
	global_load_ushort v131, v[116:117], off
	v_lshl_add_u64 v[116:117], v[116:117], 0, s[98:99]
	global_load_ushort v132, v[116:117], off
	v_lshl_add_u64 v[116:117], v[116:117], 0, s[98:99]
	global_load_ushort v133, v[116:117], off
	v_lshl_add_u64 v[116:117], v[116:117], 0, s[98:99]
	global_load_ushort v134, v[116:117], off
	v_lshl_add_u64 v[116:117], v[116:117], 0, s[98:99]
	global_load_ushort v135, v[116:117], off
	v_lshl_add_u64 v[116:117], v[116:117], 0, s[98:99]
	global_load_ushort v136, v[116:117], off
	v_lshl_add_u64 v[116:117], v[116:117], 0, s[98:99]
	global_load_ushort v137, v[116:117], off
	v_lshl_add_u64 v[116:117], v[116:117], 0, s[98:99]
	global_load_ushort v138, v[116:117], off
	v_lshl_add_u64 v[116:117], v[116:117], 0, s[98:99]
	global_load_ushort v139, v[116:117], off
	v_lshl_add_u64 v[116:117], v[116:117], 0, s[98:99]
	global_load_ushort v140, v[116:117], off
	v_lshl_add_u64 v[116:117], v[116:117], 0, s[98:99]
	global_load_ushort v141, v[116:117], off
	v_lshl_add_u64 v[116:117], v[116:117], 0, s[98:99]
	global_load_ushort v142, v[116:117], off
	v_lshl_add_u64 v[116:117], v[116:117], 0, s[98:99]
	global_load_ushort v143, v[116:117], off
	v_lshl_add_u64 v[116:117], v[116:117], 0, s[98:99]
	global_load_ushort v144, v[116:117], off
	v_lshl_add_u64 v[116:117], v[116:117], 0, s[98:99]
	global_load_ushort v145, v[116:117], off
	v_lshl_add_u64 v[116:117], v[116:117], 0, s[98:99]
	global_load_ushort v146, v[116:117], off
	v_lshl_add_u64 v[116:117], v[116:117], 0, s[98:99]
	global_load_ushort v147, v[116:117], off
	v_lshl_add_u64 v[116:117], v[116:117], 0, s[98:99]
	global_load_ushort v148, v[116:117], off
	v_lshl_add_u64 v[116:117], v[116:117], 0, s[98:99]
	global_load_ushort v149, v[116:117], off
	v_lshl_add_u64 v[116:117], v[116:117], 0, s[98:99]
	global_load_ushort v150, v[116:117], off
	v_lshl_add_u64 v[116:117], v[116:117], 0, s[98:99]
	global_load_ushort v151, v[116:117], off
	v_lshl_add_u64 v[116:117], v[116:117], 0, s[98:99]
	global_load_ushort v152, v[116:117], off
	v_lshl_add_u64 v[116:117], v[116:117], 0, s[98:99]
	global_load_ushort v153, v[116:117], off
	v_lshl_add_u64 v[116:117], v[116:117], 0, s[98:99]
	global_load_ushort v154, v[116:117], off
	v_lshl_add_u64 v[116:117], v[116:117], 0, s[98:99]
	global_load_ushort v155, v[116:117], off
	v_lshl_add_u64 v[116:117], v[116:117], 0, s[98:99]
	global_load_ushort v156, v[116:117], off
	v_lshl_add_u64 v[116:117], v[116:117], 0, s[98:99]
	global_load_ushort v157, v[116:117], off
	v_lshl_add_u64 v[116:117], v[116:117], 0, s[98:99]
	global_load_ushort v158, v[116:117], off
	v_lshl_add_u64 v[116:117], v[116:117], 0, s[98:99]
	v_mov_b32_e32 v121, 0x358637bd
	s_waitcnt vmcnt(0)
	v_mul_f32_e32 v122, v10, v11
	v_lshlrev_b32_e32 v127, 16, v127
	v_lshlrev_b32_e32 v128, 16, v128
	v_lshlrev_b32_e32 v129, 16, v129
	v_lshlrev_b32_e32 v130, 16, v130
	v_lshlrev_b32_e32 v131, 16, v131
	v_lshlrev_b32_e32 v132, 16, v132
	v_lshlrev_b32_e32 v133, 16, v133
	v_lshlrev_b32_e32 v134, 16, v134
	v_lshlrev_b32_e32 v135, 16, v135
	v_lshlrev_b32_e32 v136, 16, v136
	v_lshlrev_b32_e32 v137, 16, v137
	v_lshlrev_b32_e32 v138, 16, v138
	v_lshlrev_b32_e32 v139, 16, v139
	v_lshlrev_b32_e32 v140, 16, v140
	v_lshlrev_b32_e32 v141, 16, v141
	v_lshlrev_b32_e32 v142, 16, v142
	v_lshlrev_b32_e32 v143, 16, v143
	v_lshlrev_b32_e32 v144, 16, v144
	v_lshlrev_b32_e32 v145, 16, v145
	v_lshlrev_b32_e32 v146, 16, v146
	v_lshlrev_b32_e32 v147, 16, v147
	v_lshlrev_b32_e32 v148, 16, v148
	v_lshlrev_b32_e32 v149, 16, v149
	v_lshlrev_b32_e32 v150, 16, v150
	v_lshlrev_b32_e32 v151, 16, v151
	v_lshlrev_b32_e32 v152, 16, v152
	v_lshlrev_b32_e32 v153, 16, v153
	v_lshlrev_b32_e32 v154, 16, v154
	v_lshlrev_b32_e32 v155, 16, v155
	v_lshlrev_b32_e32 v156, 16, v156
	v_lshlrev_b32_e32 v157, 16, v157
	v_lshlrev_b32_e32 v158, 16, v158
	v_mul_f32_e32 v215, v127, v127
	v_mul_f32_e32 v216, v128, v128
	v_mul_f32_e32 v217, v129, v129
	v_mul_f32_e32 v218, v130, v130
	v_mul_f32_e32 v219, v131, v131
	v_mul_f32_e32 v220, v132, v132
	v_mul_f32_e32 v221, v133, v133
	v_mul_f32_e32 v222, v134, v134
	v_mul_f32_e32 v223, v135, v135
	v_mul_f32_e32 v224, v136, v136
	v_mul_f32_e32 v225, v137, v137
	v_mul_f32_e32 v226, v138, v138
	v_mul_f32_e32 v227, v139, v139
	v_mul_f32_e32 v228, v140, v140
	v_mul_f32_e32 v229, v141, v141
	v_mul_f32_e32 v230, v142, v142
	v_mul_f32_e32 v231, v143, v143
	v_mul_f32_e32 v232, v144, v144
	v_mul_f32_e32 v233, v145, v145
	v_mul_f32_e32 v234, v146, v146
	v_mul_f32_e32 v235, v147, v147
	v_mul_f32_e32 v236, v148, v148
	v_mul_f32_e32 v237, v149, v149
	v_mul_f32_e32 v238, v150, v150
	v_mul_f32_e32 v239, v151, v151
; DI float wave_sum(float v, int lane) {
; #pragma unroll
;   for (int o = 32; o > 0; o >>= 1) v += shx(v, o, lane);
;   return v;
; }
; DI void post_z(const Params& p, int layer) {
;     ...
;       for (int i = 0; i < 32; ++i) {
;         float ss = wave_sum(v[i] * v[i], lane);
;         float rs = rsqrtf(ss * (1.f / 64.f) + 1e-6f);
	v_mul_f32_e32 v240, v152, v152
	v_mul_f32_e32 v241, v153, v153
	v_mul_f32_e32 v242, v154, v154
	v_mul_f32_e32 v243, v155, v155
	v_mul_f32_e32 v244, v156, v156
	v_mul_f32_e32 v245, v157, v157
	v_mul_f32_e32 v246, v158, v158
	v_add_f32_dpp v215, v215, v215 quad_perm:[1,0,3,2] row_mask:0xf bank_mask:0xf
	v_add_f32_dpp v216, v216, v216 quad_perm:[1,0,3,2] row_mask:0xf bank_mask:0xf
	v_add_f32_dpp v217, v217, v217 quad_perm:[1,0,3,2] row_mask:0xf bank_mask:0xf
	v_add_f32_dpp v218, v218, v218 quad_perm:[1,0,3,2] row_mask:0xf bank_mask:0xf
	v_add_f32_dpp v219, v219, v219 quad_perm:[1,0,3,2] row_mask:0xf bank_mask:0xf
	v_add_f32_dpp v220, v220, v220 quad_perm:[1,0,3,2] row_mask:0xf bank_mask:0xf
	v_add_f32_dpp v221, v221, v221 quad_perm:[1,0,3,2] row_mask:0xf bank_mask:0xf
	v_add_f32_dpp v222, v222, v222 quad_perm:[1,0,3,2] row_mask:0xf bank_mask:0xf
	v_add_f32_dpp v223, v223, v223 quad_perm:[1,0,3,2] row_mask:0xf bank_mask:0xf
	v_add_f32_dpp v224, v224, v224 quad_perm:[1,0,3,2] row_mask:0xf bank_mask:0xf
	v_add_f32_dpp v225, v225, v225 quad_perm:[1,0,3,2] row_mask:0xf bank_mask:0xf
	v_add_f32_dpp v226, v226, v226 quad_perm:[1,0,3,2] row_mask:0xf bank_mask:0xf
	v_add_f32_dpp v227, v227, v227 quad_perm:[1,0,3,2] row_mask:0xf bank_mask:0xf
	v_add_f32_dpp v228, v228, v228 quad_perm:[1,0,3,2] row_mask:0xf bank_mask:0xf
	v_add_f32_dpp v229, v229, v229 quad_perm:[1,0,3,2] row_mask:0xf bank_mask:0xf
	v_add_f32_dpp v230, v230, v230 quad_perm:[1,0,3,2] row_mask:0xf bank_mask:0xf
	v_add_f32_dpp v231, v231, v231 quad_perm:[1,0,3,2] row_mask:0xf bank_mask:0xf
	v_add_f32_dpp v232, v232, v232 quad_perm:[1,0,3,2] row_mask:0xf bank_mask:0xf
	v_add_f32_dpp v233, v233, v233 quad_perm:[1,0,3,2] row_mask:0xf bank_mask:0xf
	v_add_f32_dpp v234, v234, v234 quad_perm:[1,0,3,2] row_mask:0xf bank_mask:0xf
	v_add_f32_dpp v235, v235, v235 quad_perm:[1,0,3,2] row_mask:0xf bank_mask:0xf
	v_add_f32_dpp v236, v236, v236 quad_perm:[1,0,3,2] row_mask:0xf bank_mask:0xf
	v_add_f32_dpp v237, v237, v237 quad_perm:[1,0,3,2] row_mask:0xf bank_mask:0xf
	v_add_f32_dpp v238, v238, v238 quad_perm:[1,0,3,2] row_mask:0xf bank_mask:0xf
	v_add_f32_dpp v239, v239, v239 quad_perm:[1,0,3,2] row_mask:0xf bank_mask:0xf
	v_add_f32_dpp v240, v240, v240 quad_perm:[1,0,3,2] row_mask:0xf bank_mask:0xf
	v_add_f32_dpp v241, v241, v241 quad_perm:[1,0,3,2] row_mask:0xf bank_mask:0xf
	v_add_f32_dpp v242, v242, v242 quad_perm:[1,0,3,2] row_mask:0xf bank_mask:0xf
	v_add_f32_dpp v243, v243, v243 quad_perm:[1,0,3,2] row_mask:0xf bank_mask:0xf
	v_add_f32_dpp v244, v244, v244 quad_perm:[1,0,3,2] row_mask:0xf bank_mask:0xf
	v_add_f32_dpp v245, v245, v245 quad_perm:[1,0,3,2] row_mask:0xf bank_mask:0xf
	v_add_f32_dpp v246, v246, v246 quad_perm:[1,0,3,2] row_mask:0xf bank_mask:0xf
	v_add_f32_dpp v215, v215, v215 quad_perm:[2,3,0,1] row_mask:0xf bank_mask:0xf
	v_add_f32_dpp v216, v216, v216 quad_perm:[2,3,0,1] row_mask:0xf bank_mask:0xf
	v_add_f32_dpp v217, v217, v217 quad_perm:[2,3,0,1] row_mask:0xf bank_mask:0xf
	v_add_f32_dpp v218, v218, v218 quad_perm:[2,3,0,1] row_mask:0xf bank_mask:0xf
	v_add_f32_dpp v219, v219, v219 quad_perm:[2,3,0,1] row_mask:0xf bank_mask:0xf
	v_add_f32_dpp v220, v220, v220 quad_perm:[2,3,0,1] row_mask:0xf bank_mask:0xf
	v_add_f32_dpp v221, v221, v221 quad_perm:[2,3,0,1] row_mask:0xf bank_mask:0xf
	v_add_f32_dpp v222, v222, v222 quad_perm:[2,3,0,1] row_mask:0xf bank_mask:0xf
	v_add_f32_dpp v223, v223, v223 quad_perm:[2,3,0,1] row_mask:0xf bank_mask:0xf
	v_add_f32_dpp v224, v224, v224 quad_perm:[2,3,0,1] row_mask:0xf bank_mask:0xf
	v_add_f32_dpp v225, v225, v225 quad_perm:[2,3,0,1] row_mask:0xf bank_mask:0xf
	v_add_f32_dpp v226, v226, v226 quad_perm:[2,3,0,1] row_mask:0xf bank_mask:0xf
	v_add_f32_dpp v227, v227, v227 quad_perm:[2,3,0,1] row_mask:0xf bank_mask:0xf
	v_add_f32_dpp v228, v228, v228 quad_perm:[2,3,0,1] row_mask:0xf bank_mask:0xf
	v_add_f32_dpp v229, v229, v229 quad_perm:[2,3,0,1] row_mask:0xf bank_mask:0xf
	v_add_f32_dpp v230, v230, v230 quad_perm:[2,3,0,1] row_mask:0xf bank_mask:0xf
	v_add_f32_dpp v231, v231, v231 quad_perm:[2,3,0,1] row_mask:0xf bank_mask:0xf
	v_add_f32_dpp v232, v232, v232 quad_perm:[2,3,0,1] row_mask:0xf bank_mask:0xf
	v_add_f32_dpp v233, v233, v233 quad_perm:[2,3,0,1] row_mask:0xf bank_mask:0xf
	v_add_f32_dpp v234, v234, v234 quad_perm:[2,3,0,1] row_mask:0xf bank_mask:0xf
	v_add_f32_dpp v235, v235, v235 quad_perm:[2,3,0,1] row_mask:0xf bank_mask:0xf
	v_add_f32_dpp v236, v236, v236 quad_perm:[2,3,0,1] row_mask:0xf bank_mask:0xf
	v_add_f32_dpp v237, v237, v237 quad_perm:[2,3,0,1] row_mask:0xf bank_mask:0xf
	v_add_f32_dpp v238, v238, v238 quad_perm:[2,3,0,1] row_mask:0xf bank_mask:0xf
	v_add_f32_dpp v239, v239, v239 quad_perm:[2,3,0,1] row_mask:0xf bank_mask:0xf
	v_add_f32_dpp v240, v240, v240 quad_perm:[2,3,0,1] row_mask:0xf bank_mask:0xf
	v_add_f32_dpp v241, v241, v241 quad_perm:[2,3,0,1] row_mask:0xf bank_mask:0xf
	v_add_f32_dpp v242, v242, v242 quad_perm:[2,3,0,1] row_mask:0xf bank_mask:0xf
	v_add_f32_dpp v243, v243, v243 quad_perm:[2,3,0,1] row_mask:0xf bank_mask:0xf
	v_add_f32_dpp v244, v244, v244 quad_perm:[2,3,0,1] row_mask:0xf bank_mask:0xf
	v_add_f32_dpp v245, v245, v245 quad_perm:[2,3,0,1] row_mask:0xf bank_mask:0xf
	v_add_f32_dpp v246, v246, v246 quad_perm:[2,3,0,1] row_mask:0xf bank_mask:0xf
	v_add_f32_dpp v215, v215, v215 row_half_mirror row_mask:0xf bank_mask:0xf
	v_add_f32_dpp v216, v216, v216 row_half_mirror row_mask:0xf bank_mask:0xf
	v_add_f32_dpp v217, v217, v217 row_half_mirror row_mask:0xf bank_mask:0xf
	v_add_f32_dpp v218, v218, v218 row_half_mirror row_mask:0xf bank_mask:0xf
	v_add_f32_dpp v219, v219, v219 row_half_mirror row_mask:0xf bank_mask:0xf
; DI float wave_sum(float v, int lane) {
; #pragma unroll
;   for (int o = 32; o > 0; o >>= 1) v += shx(v, o, lane);
;   return v;
; }
	v_add_f32_dpp v220, v220, v220 row_half_mirror row_mask:0xf bank_mask:0xf
	v_add_f32_dpp v221, v221, v221 row_half_mirror row_mask:0xf bank_mask:0xf
	v_add_f32_dpp v222, v222, v222 row_half_mirror row_mask:0xf bank_mask:0xf
	v_add_f32_dpp v223, v223, v223 row_half_mirror row_mask:0xf bank_mask:0xf
	v_add_f32_dpp v224, v224, v224 row_half_mirror row_mask:0xf bank_mask:0xf
	v_add_f32_dpp v225, v225, v225 row_half_mirror row_mask:0xf bank_mask:0xf
	v_add_f32_dpp v226, v226, v226 row_half_mirror row_mask:0xf bank_mask:0xf
	v_add_f32_dpp v227, v227, v227 row_half_mirror row_mask:0xf bank_mask:0xf
	v_add_f32_dpp v228, v228, v228 row_half_mirror row_mask:0xf bank_mask:0xf
	v_add_f32_dpp v229, v229, v229 row_half_mirror row_mask:0xf bank_mask:0xf
	v_add_f32_dpp v230, v230, v230 row_half_mirror row_mask:0xf bank_mask:0xf
	v_add_f32_dpp v231, v231, v231 row_half_mirror row_mask:0xf bank_mask:0xf
	v_add_f32_dpp v232, v232, v232 row_half_mirror row_mask:0xf bank_mask:0xf
	v_add_f32_dpp v233, v233, v233 row_half_mirror row_mask:0xf bank_mask:0xf
	v_add_f32_dpp v234, v234, v234 row_half_mirror row_mask:0xf bank_mask:0xf
	v_add_f32_dpp v235, v235, v235 row_half_mirror row_mask:0xf bank_mask:0xf
	v_add_f32_dpp v236, v236, v236 row_half_mirror row_mask:0xf bank_mask:0xf
	v_add_f32_dpp v237, v237, v237 row_half_mirror row_mask:0xf bank_mask:0xf
	v_add_f32_dpp v238, v238, v238 row_half_mirror row_mask:0xf bank_mask:0xf
	v_add_f32_dpp v239, v239, v239 row_half_mirror row_mask:0xf bank_mask:0xf
	v_add_f32_dpp v240, v240, v240 row_half_mirror row_mask:0xf bank_mask:0xf
	v_add_f32_dpp v241, v241, v241 row_half_mirror row_mask:0xf bank_mask:0xf
	v_add_f32_dpp v242, v242, v242 row_half_mirror row_mask:0xf bank_mask:0xf
	v_add_f32_dpp v243, v243, v243 row_half_mirror row_mask:0xf bank_mask:0xf
	v_add_f32_dpp v244, v244, v244 row_half_mirror row_mask:0xf bank_mask:0xf
	v_add_f32_dpp v245, v245, v245 row_half_mirror row_mask:0xf bank_mask:0xf
	v_add_f32_dpp v246, v246, v246 row_half_mirror row_mask:0xf bank_mask:0xf
	v_add_f32_dpp v215, v215, v215 row_mirror row_mask:0xf bank_mask:0xf
	v_add_f32_dpp v216, v216, v216 row_mirror row_mask:0xf bank_mask:0xf
	v_add_f32_dpp v217, v217, v217 row_mirror row_mask:0xf bank_mask:0xf
	v_add_f32_dpp v218, v218, v218 row_mirror row_mask:0xf bank_mask:0xf
	v_add_f32_dpp v219, v219, v219 row_mirror row_mask:0xf bank_mask:0xf
	v_add_f32_dpp v220, v220, v220 row_mirror row_mask:0xf bank_mask:0xf
	v_add_f32_dpp v221, v221, v221 row_mirror row_mask:0xf bank_mask:0xf
	v_add_f32_dpp v222, v222, v222 row_mirror row_mask:0xf bank_mask:0xf
	v_add_f32_dpp v223, v223, v223 row_mirror row_mask:0xf bank_mask:0xf
	v_add_f32_dpp v224, v224, v224 row_mirror row_mask:0xf bank_mask:0xf
	v_add_f32_dpp v225, v225, v225 row_mirror row_mask:0xf bank_mask:0xf
	v_add_f32_dpp v226, v226, v226 row_mirror row_mask:0xf bank_mask:0xf
	v_add_f32_dpp v227, v227, v227 row_mirror row_mask:0xf bank_mask:0xf
	v_add_f32_dpp v228, v228, v228 row_mirror row_mask:0xf bank_mask:0xf
	v_add_f32_dpp v229, v229, v229 row_mirror row_mask:0xf bank_mask:0xf
	v_add_f32_dpp v230, v230, v230 row_mirror row_mask:0xf bank_mask:0xf
	v_add_f32_dpp v231, v231, v231 row_mirror row_mask:0xf bank_mask:0xf
	v_add_f32_dpp v232, v232, v232 row_mirror row_mask:0xf bank_mask:0xf
	v_add_f32_dpp v233, v233, v233 row_mirror row_mask:0xf bank_mask:0xf
	v_add_f32_dpp v234, v234, v234 row_mirror row_mask:0xf bank_mask:0xf
	v_add_f32_dpp v235, v235, v235 row_mirror row_mask:0xf bank_mask:0xf
	v_add_f32_dpp v236, v236, v236 row_mirror row_mask:0xf bank_mask:0xf
	v_add_f32_dpp v237, v237, v237 row_mirror row_mask:0xf bank_mask:0xf
	v_add_f32_dpp v238, v238, v238 row_mirror row_mask:0xf bank_mask:0xf
	v_add_f32_dpp v239, v239, v239 row_mirror row_mask:0xf bank_mask:0xf
	v_add_f32_dpp v240, v240, v240 row_mirror row_mask:0xf bank_mask:0xf
	v_add_f32_dpp v241, v241, v241 row_mirror row_mask:0xf bank_mask:0xf
	v_add_f32_dpp v242, v242, v242 row_mirror row_mask:0xf bank_mask:0xf
	v_add_f32_dpp v243, v243, v243 row_mirror row_mask:0xf bank_mask:0xf
	v_add_f32_dpp v244, v244, v244 row_mirror row_mask:0xf bank_mask:0xf
	v_add_f32_dpp v245, v245, v245 row_mirror row_mask:0xf bank_mask:0xf
	v_add_f32_dpp v246, v246, v246 row_mirror row_mask:0xf bank_mask:0xf
	v_add_f32_dpp v215, v215, v215 row_bcast:15 row_mask:0xa bank_mask:0xf
	v_add_f32_dpp v216, v216, v216 row_bcast:15 row_mask:0xa bank_mask:0xf
	v_add_f32_dpp v217, v217, v217 row_bcast:15 row_mask:0xa bank_mask:0xf
	v_add_f32_dpp v218, v218, v218 row_bcast:15 row_mask:0xa bank_mask:0xf
	v_add_f32_dpp v219, v219, v219 row_bcast:15 row_mask:0xa bank_mask:0xf
	v_add_f32_dpp v220, v220, v220 row_bcast:15 row_mask:0xa bank_mask:0xf
	v_add_f32_dpp v221, v221, v221 row_bcast:15 row_mask:0xa bank_mask:0xf
	v_add_f32_dpp v222, v222, v222 row_bcast:15 row_mask:0xa bank_mask:0xf
	v_add_f32_dpp v223, v223, v223 row_bcast:15 row_mask:0xa bank_mask:0xf
	v_add_f32_dpp v224, v224, v224 row_bcast:15 row_mask:0xa bank_mask:0xf
	v_add_f32_dpp v225, v225, v225 row_bcast:15 row_mask:0xa bank_mask:0xf
	v_add_f32_dpp v226, v226, v226 row_bcast:15 row_mask:0xa bank_mask:0xf
	v_add_f32_dpp v227, v227, v227 row_bcast:15 row_mask:0xa bank_mask:0xf
	v_add_f32_dpp v228, v228, v228 row_bcast:15 row_mask:0xa bank_mask:0xf
	v_add_f32_dpp v229, v229, v229 row_bcast:15 row_mask:0xa bank_mask:0xf
	v_add_f32_dpp v230, v230, v230 row_bcast:15 row_mask:0xa bank_mask:0xf
	v_add_f32_dpp v231, v231, v231 row_bcast:15 row_mask:0xa bank_mask:0xf
	v_add_f32_dpp v232, v232, v232 row_bcast:15 row_mask:0xa bank_mask:0xf
	v_add_f32_dpp v233, v233, v233 row_bcast:15 row_mask:0xa bank_mask:0xf
; DI float wave_sum(float v, int lane) {
; #pragma unroll
;   for (int o = 32; o > 0; o >>= 1) v += shx(v, o, lane);
;   return v;
; }
; DI void post_z(const Params& p, int layer) {
;     ...
;         float ss = wave_sum(v[i] * v[i], lane);
;         float rs = rsqrtf(ss * (1.f / 64.f) + 1e-6f);
	v_add_f32_dpp v234, v234, v234 row_bcast:15 row_mask:0xa bank_mask:0xf
	v_add_f32_dpp v235, v235, v235 row_bcast:15 row_mask:0xa bank_mask:0xf
	v_add_f32_dpp v236, v236, v236 row_bcast:15 row_mask:0xa bank_mask:0xf
	v_add_f32_dpp v237, v237, v237 row_bcast:15 row_mask:0xa bank_mask:0xf
	v_add_f32_dpp v238, v238, v238 row_bcast:15 row_mask:0xa bank_mask:0xf
	v_add_f32_dpp v239, v239, v239 row_bcast:15 row_mask:0xa bank_mask:0xf
	v_add_f32_dpp v240, v240, v240 row_bcast:15 row_mask:0xa bank_mask:0xf
	v_add_f32_dpp v241, v241, v241 row_bcast:15 row_mask:0xa bank_mask:0xf
	v_add_f32_dpp v242, v242, v242 row_bcast:15 row_mask:0xa bank_mask:0xf
	v_add_f32_dpp v243, v243, v243 row_bcast:15 row_mask:0xa bank_mask:0xf
	v_add_f32_dpp v244, v244, v244 row_bcast:15 row_mask:0xa bank_mask:0xf
	v_add_f32_dpp v245, v245, v245 row_bcast:15 row_mask:0xa bank_mask:0xf
	v_add_f32_dpp v246, v246, v246 row_bcast:15 row_mask:0xa bank_mask:0xf
	v_add_f32_dpp v215, v215, v215 row_bcast:31 row_mask:0xc bank_mask:0xf
	v_add_f32_dpp v216, v216, v216 row_bcast:31 row_mask:0xc bank_mask:0xf
	v_add_f32_dpp v217, v217, v217 row_bcast:31 row_mask:0xc bank_mask:0xf
	v_add_f32_dpp v218, v218, v218 row_bcast:31 row_mask:0xc bank_mask:0xf
	v_add_f32_dpp v219, v219, v219 row_bcast:31 row_mask:0xc bank_mask:0xf
	v_add_f32_dpp v220, v220, v220 row_bcast:31 row_mask:0xc bank_mask:0xf
	v_add_f32_dpp v221, v221, v221 row_bcast:31 row_mask:0xc bank_mask:0xf
	v_add_f32_dpp v222, v222, v222 row_bcast:31 row_mask:0xc bank_mask:0xf
	v_add_f32_dpp v223, v223, v223 row_bcast:31 row_mask:0xc bank_mask:0xf
	v_add_f32_dpp v224, v224, v224 row_bcast:31 row_mask:0xc bank_mask:0xf
	v_add_f32_dpp v225, v225, v225 row_bcast:31 row_mask:0xc bank_mask:0xf
	v_add_f32_dpp v226, v226, v226 row_bcast:31 row_mask:0xc bank_mask:0xf
	v_add_f32_dpp v227, v227, v227 row_bcast:31 row_mask:0xc bank_mask:0xf
	v_add_f32_dpp v228, v228, v228 row_bcast:31 row_mask:0xc bank_mask:0xf
	v_add_f32_dpp v229, v229, v229 row_bcast:31 row_mask:0xc bank_mask:0xf
	v_add_f32_dpp v230, v230, v230 row_bcast:31 row_mask:0xc bank_mask:0xf
	v_add_f32_dpp v231, v231, v231 row_bcast:31 row_mask:0xc bank_mask:0xf
	v_add_f32_dpp v232, v232, v232 row_bcast:31 row_mask:0xc bank_mask:0xf
	v_add_f32_dpp v233, v233, v233 row_bcast:31 row_mask:0xc bank_mask:0xf
	v_add_f32_dpp v234, v234, v234 row_bcast:31 row_mask:0xc bank_mask:0xf
	v_add_f32_dpp v235, v235, v235 row_bcast:31 row_mask:0xc bank_mask:0xf
	v_add_f32_dpp v236, v236, v236 row_bcast:31 row_mask:0xc bank_mask:0xf
	v_add_f32_dpp v237, v237, v237 row_bcast:31 row_mask:0xc bank_mask:0xf
	v_add_f32_dpp v238, v238, v238 row_bcast:31 row_mask:0xc bank_mask:0xf
	v_add_f32_dpp v239, v239, v239 row_bcast:31 row_mask:0xc bank_mask:0xf
	v_add_f32_dpp v240, v240, v240 row_bcast:31 row_mask:0xc bank_mask:0xf
	v_add_f32_dpp v241, v241, v241 row_bcast:31 row_mask:0xc bank_mask:0xf
	v_add_f32_dpp v242, v242, v242 row_bcast:31 row_mask:0xc bank_mask:0xf
	v_add_f32_dpp v243, v243, v243 row_bcast:31 row_mask:0xc bank_mask:0xf
	v_add_f32_dpp v244, v244, v244 row_bcast:31 row_mask:0xc bank_mask:0xf
	v_add_f32_dpp v245, v245, v245 row_bcast:31 row_mask:0xc bank_mask:0xf
	v_add_f32_dpp v246, v246, v246 row_bcast:31 row_mask:0xc bank_mask:0xf
	s_nop 1
	v_readlane_b32 s46, v215, 63
	v_readlane_b32 s47, v216, 63
	v_readlane_b32 s48, v217, 63
	v_readlane_b32 s49, v218, 63
	v_readlane_b32 s50, v219, 63
	v_readlane_b32 s51, v220, 63
	v_readlane_b32 s52, v221, 63
	v_readlane_b32 s53, v222, 63
	v_readlane_b32 s54, v223, 63
	v_readlane_b32 s55, v224, 63
	v_readlane_b32 s56, v225, 63
	v_readlane_b32 s57, v226, 63
	v_readlane_b32 s58, v227, 63
	v_readlane_b32 s59, v228, 63
	v_readlane_b32 s60, v229, 63
	v_readlane_b32 s61, v230, 63
	v_readlane_b32 s62, v231, 63
	v_readlane_b32 s63, v232, 63
	v_readlane_b32 s64, v233, 63
	v_readlane_b32 s65, v234, 63
	v_readlane_b32 s66, v235, 63
	v_readlane_b32 s67, v236, 63
	v_readlane_b32 s68, v237, 63
	v_readlane_b32 s69, v238, 63
	v_readlane_b32 s70, v239, 63
	v_readlane_b32 s71, v240, 63
	v_readlane_b32 s72, v241, 63
	v_readlane_b32 s73, v242, 63
	v_readlane_b32 s74, v243, 63
	v_readlane_b32 s75, v244, 63
	v_readlane_b32 s76, v245, 63
	v_readlane_b32 s77, v246, 63
	v_mov_b32_e32 v215, s46
	v_mov_b32_e32 v216, s47
	v_mov_b32_e32 v217, s48
	v_mov_b32_e32 v218, s49
	v_mov_b32_e32 v219, s50
	v_mov_b32_e32 v220, s51
	v_mov_b32_e32 v221, s52
	v_mov_b32_e32 v222, s53
	v_mov_b32_e32 v223, s54
	v_mov_b32_e32 v224, s55
	v_mov_b32_e32 v225, s56
	v_mov_b32_e32 v226, s57
	v_mov_b32_e32 v227, s58
	v_mov_b32_e32 v228, s59
	v_mov_b32_e32 v229, s60
	v_mov_b32_e32 v230, s61
	v_mov_b32_e32 v231, s62
	v_mov_b32_e32 v232, s63
	v_mov_b32_e32 v233, s64
	v_mov_b32_e32 v234, s65
	v_mov_b32_e32 v235, s66
	v_mov_b32_e32 v236, s67
	v_mov_b32_e32 v237, s68
	v_mov_b32_e32 v238, s69
	v_mov_b32_e32 v239, s70
	v_mov_b32_e32 v240, s71
	v_mov_b32_e32 v241, s72
	v_mov_b32_e32 v242, s73
	v_mov_b32_e32 v243, s74
	v_mov_b32_e32 v244, s75
	v_mov_b32_e32 v245, s76
	v_mov_b32_e32 v246, s77
	v_fmamk_f32 v215, v215, 0x3c800000, v121
	v_fmamk_f32 v216, v216, 0x3c800000, v121
	v_fmamk_f32 v217, v217, 0x3c800000, v121
	v_fmamk_f32 v218, v218, 0x3c800000, v121
	v_fmamk_f32 v219, v219, 0x3c800000, v121
	v_fmamk_f32 v220, v220, 0x3c800000, v121
	v_fmamk_f32 v221, v221, 0x3c800000, v121
	v_fmamk_f32 v222, v222, 0x3c800000, v121
	v_fmamk_f32 v223, v223, 0x3c800000, v121
	v_fmamk_f32 v224, v224, 0x3c800000, v121
	v_fmamk_f32 v225, v225, 0x3c800000, v121
	v_fmamk_f32 v226, v226, 0x3c800000, v121
	v_fmamk_f32 v227, v227, 0x3c800000, v121
	v_fmamk_f32 v228, v228, 0x3c800000, v121
	v_fmamk_f32 v229, v229, 0x3c800000, v121
; DI bf16_t f2bf(float a) { return (bf16_t)(pack2(a, 0.f) & 0xffffu); }
; DI void post_z(const Params& p, int layer) {
;     ...
;         float rs = rsqrtf(ss * (1.f / 64.f) + 1e-6f);
;         zr[(size_t)i * ZS + colbase + lane] = f2bf(v[i] * rs * gv);
	v_fmamk_f32 v230, v230, 0x3c800000, v121
	v_fmamk_f32 v231, v231, 0x3c800000, v121
	v_fmamk_f32 v232, v232, 0x3c800000, v121
	v_fmamk_f32 v233, v233, 0x3c800000, v121
	v_fmamk_f32 v234, v234, 0x3c800000, v121
	v_fmamk_f32 v235, v235, 0x3c800000, v121
	v_fmamk_f32 v236, v236, 0x3c800000, v121
	v_fmamk_f32 v237, v237, 0x3c800000, v121
	v_fmamk_f32 v238, v238, 0x3c800000, v121
	v_fmamk_f32 v239, v239, 0x3c800000, v121
	v_fmamk_f32 v240, v240, 0x3c800000, v121
	v_fmamk_f32 v241, v241, 0x3c800000, v121
	v_fmamk_f32 v242, v242, 0x3c800000, v121
	v_fmamk_f32 v243, v243, 0x3c800000, v121
	v_fmamk_f32 v244, v244, 0x3c800000, v121
	v_fmamk_f32 v245, v245, 0x3c800000, v121
	v_fmamk_f32 v246, v246, 0x3c800000, v121
	v_rsq_f32_e32 v215, v215
	v_rsq_f32_e32 v216, v216
	v_rsq_f32_e32 v217, v217
	v_rsq_f32_e32 v218, v218
	v_rsq_f32_e32 v219, v219
	v_rsq_f32_e32 v220, v220
	v_rsq_f32_e32 v221, v221
	v_rsq_f32_e32 v222, v222
	v_rsq_f32_e32 v223, v223
	v_rsq_f32_e32 v224, v224
	v_rsq_f32_e32 v225, v225
	v_rsq_f32_e32 v226, v226
	v_rsq_f32_e32 v227, v227
	v_rsq_f32_e32 v228, v228
	v_rsq_f32_e32 v229, v229
	v_rsq_f32_e32 v230, v230
	v_rsq_f32_e32 v231, v231
	v_rsq_f32_e32 v232, v232
	v_rsq_f32_e32 v233, v233
	v_rsq_f32_e32 v234, v234
	v_rsq_f32_e32 v235, v235
	v_rsq_f32_e32 v236, v236
	v_rsq_f32_e32 v237, v237
	v_rsq_f32_e32 v238, v238
	v_rsq_f32_e32 v239, v239
	v_rsq_f32_e32 v240, v240
	v_rsq_f32_e32 v241, v241
	v_rsq_f32_e32 v242, v242
	v_rsq_f32_e32 v243, v243
	v_rsq_f32_e32 v244, v244
	v_rsq_f32_e32 v245, v245
	v_rsq_f32_e32 v246, v246
	v_mul_f32_e32 v127, v215, v127
	v_mul_f32_e32 v128, v216, v128
	v_mul_f32_e32 v129, v217, v129
	v_mul_f32_e32 v130, v218, v130
	v_mul_f32_e32 v131, v219, v131
	v_mul_f32_e32 v132, v220, v132
	v_mul_f32_e32 v133, v221, v133
	v_mul_f32_e32 v134, v222, v134
	v_mul_f32_e32 v135, v223, v135
	v_mul_f32_e32 v136, v224, v136
	v_mul_f32_e32 v137, v225, v137
	v_mul_f32_e32 v138, v226, v138
	v_mul_f32_e32 v139, v227, v139
	v_mul_f32_e32 v140, v228, v140
	v_mul_f32_e32 v141, v229, v141
	v_mul_f32_e32 v142, v230, v142
	v_mul_f32_e32 v143, v231, v143
	v_mul_f32_e32 v144, v232, v144
	v_mul_f32_e32 v145, v233, v145
	v_mul_f32_e32 v146, v234, v146
	v_mul_f32_e32 v147, v235, v147
	v_mul_f32_e32 v148, v236, v148
	v_mul_f32_e32 v149, v237, v149
	v_mul_f32_e32 v150, v238, v150
	v_mul_f32_e32 v151, v239, v151
	v_mul_f32_e32 v152, v240, v152
	v_mul_f32_e32 v153, v241, v153
	v_mul_f32_e32 v154, v242, v154
	v_mul_f32_e32 v155, v243, v155
	v_mul_f32_e32 v156, v244, v156
	v_mul_f32_e32 v157, v245, v157
	v_mul_f32_e32 v158, v246, v158
	v_mul_f32_e32 v127, v122, v127
	v_mul_f32_e32 v128, v122, v128
	v_mul_f32_e32 v129, v122, v129
	v_mul_f32_e32 v130, v122, v130
	v_mul_f32_e32 v131, v122, v131
	v_mul_f32_e32 v132, v122, v132
	v_mul_f32_e32 v133, v122, v133
	v_mul_f32_e32 v134, v122, v134
	v_mul_f32_e32 v135, v122, v135
	v_mul_f32_e32 v136, v122, v136
	v_mul_f32_e32 v137, v122, v137
	v_mul_f32_e32 v138, v122, v138
	v_mul_f32_e32 v139, v122, v139
	v_mul_f32_e32 v140, v122, v140
	v_mul_f32_e32 v141, v122, v141
	v_mul_f32_e32 v142, v122, v142
	v_mul_f32_e32 v143, v122, v143
	v_mul_f32_e32 v144, v122, v144
	v_mul_f32_e32 v145, v122, v145
	v_mul_f32_e32 v146, v122, v146
	v_mul_f32_e32 v147, v122, v147
	v_mul_f32_e32 v148, v122, v148
	v_mul_f32_e32 v149, v122, v149
	v_mul_f32_e32 v150, v122, v150
	v_mul_f32_e32 v151, v122, v151
	v_mul_f32_e32 v152, v122, v152
	v_mul_f32_e32 v153, v122, v153
	v_mul_f32_e32 v154, v122, v154
	v_mul_f32_e32 v155, v122, v155
	v_mul_f32_e32 v156, v122, v156
	v_mul_f32_e32 v157, v122, v157
	v_mul_f32_e32 v158, v122, v158
	v_cvt_pk_bf16_f32 v127, v127, s0
	v_cvt_pk_bf16_f32 v128, v128, s0
	v_cvt_pk_bf16_f32 v129, v129, s0
	v_cvt_pk_bf16_f32 v130, v130, s0
	v_cvt_pk_bf16_f32 v131, v131, s0
	v_cvt_pk_bf16_f32 v132, v132, s0
	v_cvt_pk_bf16_f32 v133, v133, s0
; DI bf16_t f2bf(float a) { return (bf16_t)(pack2(a, 0.f) & 0xffffu); }
; DI void post_z(const Params& p, int layer) {
;     ...
;       for (int i = 0; i < 32; ++i) {
;         float ss = wave_sum(v[i] * v[i], lane);
;         float rs = rsqrtf(ss * (1.f / 64.f) + 1e-6f);
;         zr[(size_t)i * ZS + colbase + lane] = f2bf(v[i] * rs * gv);
;       }
	v_cvt_pk_bf16_f32 v134, v134, s0
	v_cvt_pk_bf16_f32 v135, v135, s0
	v_cvt_pk_bf16_f32 v136, v136, s0
	v_cvt_pk_bf16_f32 v137, v137, s0
	v_cvt_pk_bf16_f32 v138, v138, s0
	v_cvt_pk_bf16_f32 v139, v139, s0
	v_cvt_pk_bf16_f32 v140, v140, s0
	v_cvt_pk_bf16_f32 v141, v141, s0
	v_cvt_pk_bf16_f32 v142, v142, s0
	v_cvt_pk_bf16_f32 v143, v143, s0
	v_cvt_pk_bf16_f32 v144, v144, s0
	v_cvt_pk_bf16_f32 v145, v145, s0
	v_cvt_pk_bf16_f32 v146, v146, s0
	v_cvt_pk_bf16_f32 v147, v147, s0
	v_cvt_pk_bf16_f32 v148, v148, s0
	v_cvt_pk_bf16_f32 v149, v149, s0
	v_cvt_pk_bf16_f32 v150, v150, s0
	v_cvt_pk_bf16_f32 v151, v151, s0
	v_cvt_pk_bf16_f32 v152, v152, s0
	v_cvt_pk_bf16_f32 v153, v153, s0
	v_cvt_pk_bf16_f32 v154, v154, s0
	v_cvt_pk_bf16_f32 v155, v155, s0
	v_cvt_pk_bf16_f32 v156, v156, s0
	v_cvt_pk_bf16_f32 v157, v157, s0
	v_cvt_pk_bf16_f32 v158, v158, s0
	global_store_short v[118:119], v127, off
	v_lshl_add_u64 v[118:119], v[118:119], 0, s[98:99]
	global_store_short v[118:119], v128, off
	v_lshl_add_u64 v[118:119], v[118:119], 0, s[98:99]
	global_store_short v[118:119], v129, off
	v_lshl_add_u64 v[118:119], v[118:119], 0, s[98:99]
	global_store_short v[118:119], v130, off
	v_lshl_add_u64 v[118:119], v[118:119], 0, s[98:99]
	global_store_short v[118:119], v131, off
	v_lshl_add_u64 v[118:119], v[118:119], 0, s[98:99]
	global_store_short v[118:119], v132, off
	v_lshl_add_u64 v[118:119], v[118:119], 0, s[98:99]
	global_store_short v[118:119], v133, off
	v_lshl_add_u64 v[118:119], v[118:119], 0, s[98:99]
	global_store_short v[118:119], v134, off
	v_lshl_add_u64 v[118:119], v[118:119], 0, s[98:99]
	global_store_short v[118:119], v135, off
	v_lshl_add_u64 v[118:119], v[118:119], 0, s[98:99]
	global_store_short v[118:119], v136, off
	v_lshl_add_u64 v[118:119], v[118:119], 0, s[98:99]
	global_store_short v[118:119], v137, off
	v_lshl_add_u64 v[118:119], v[118:119], 0, s[98:99]
	global_store_short v[118:119], v138, off
	v_lshl_add_u64 v[118:119], v[118:119], 0, s[98:99]
	global_store_short v[118:119], v139, off
	v_lshl_add_u64 v[118:119], v[118:119], 0, s[98:99]
	global_store_short v[118:119], v140, off
	v_lshl_add_u64 v[118:119], v[118:119], 0, s[98:99]
	global_store_short v[118:119], v141, off
	v_lshl_add_u64 v[118:119], v[118:119], 0, s[98:99]
	global_store_short v[118:119], v142, off
	v_lshl_add_u64 v[118:119], v[118:119], 0, s[98:99]
	global_store_short v[118:119], v143, off
	v_lshl_add_u64 v[118:119], v[118:119], 0, s[98:99]
	global_store_short v[118:119], v144, off
	v_lshl_add_u64 v[118:119], v[118:119], 0, s[98:99]
	global_store_short v[118:119], v145, off
	v_lshl_add_u64 v[118:119], v[118:119], 0, s[98:99]
	global_store_short v[118:119], v146, off
	v_lshl_add_u64 v[118:119], v[118:119], 0, s[98:99]
	global_store_short v[118:119], v147, off
	v_lshl_add_u64 v[118:119], v[118:119], 0, s[98:99]
	global_store_short v[118:119], v148, off
	v_lshl_add_u64 v[118:119], v[118:119], 0, s[98:99]
	global_store_short v[118:119], v149, off
	v_lshl_add_u64 v[118:119], v[118:119], 0, s[98:99]
	global_store_short v[118:119], v150, off
	v_lshl_add_u64 v[118:119], v[118:119], 0, s[98:99]
	global_store_short v[118:119], v151, off
	v_lshl_add_u64 v[118:119], v[118:119], 0, s[98:99]
	global_store_short v[118:119], v152, off
	v_lshl_add_u64 v[118:119], v[118:119], 0, s[98:99]
	global_store_short v[118:119], v153, off
	v_lshl_add_u64 v[118:119], v[118:119], 0, s[98:99]
	global_store_short v[118:119], v154, off
	v_lshl_add_u64 v[118:119], v[118:119], 0, s[98:99]
	global_store_short v[118:119], v155, off
	v_lshl_add_u64 v[118:119], v[118:119], 0, s[98:99]
	global_store_short v[118:119], v156, off
	v_lshl_add_u64 v[118:119], v[118:119], 0, s[98:99]
	global_store_short v[118:119], v157, off
	v_lshl_add_u64 v[118:119], v[118:119], 0, s[98:99]
	global_store_short v[118:119], v158, off
	v_lshl_add_u64 v[118:119], v[118:119], 0, s[98:99]
